# short-conv gate phase: the 48 per-lane conv taps are loaded once per phase instead of 8 dependent load/wait groups per row
# speedup vs baseline: 1.0349x; 1.0139x over previous
; __device__ __forceinline__ unsigned cvt_pk_bf16(float lo, float hi) { unsigned r; asm volatile("v_cvt_pk_bf16_f32 %0, %1, %2" : "=v"(r) : "v"(lo), "v"(hi)); return r; }
; __device__ __forceinline__ float bflo(unsigned w) { return __uint_as_float(w << 16); }
; __device__ __forceinline__ float bfhi(unsigned w) { return __uint_as_float(w & 0xffff0000u); }
; __device__ __forceinline__ void convgate_phase(const bf16_t* U, bf16_t* H, int rows, const float* ck, int gw, int NGW, int lane) {
;     ...
; #pragma unroll
;         for (int hf = 0; hf < 2; ++hf) {
;             const int c0 = lane * 16 + hf * 8;
;             bq[hf] = *(const u32x4*)(ur + c0); cq[hf] = *(const u32x4*)(ur + 1024 + c0); vq[hf] = *(const u32x4*)(ur + 2048 + c0);
;             cp[hf] = (u32x4){0, 0, 0, 0}; vp[hf] = cp[hf]; cn[hf] = cp[hf]; vn[hf] = cp[hf];
;             if (hasp) { cp[hf] = *(const u32x4*)(ur - 3072 + 1024 + c0); vp[hf] = *(const u32x4*)(ur - 3072 + 2048 + c0); }
;             if (hasn) { cn[hf] = *(const u32x4*)(ur + 3072 + 1024 + c0); vn[hf] = *(const u32x4*)(ur + 3072 + 2048 + c0); }
;         }
; #pragma unroll
;         for (int hf = 0; hf < 2; ++hf) {
;             const int c0 = lane * 16 + hf * 8;
;             u32x4 ow;
; #pragma unroll
;             for (int e = 0; e < 4; ++e) {
;                 const f32x2 w0 = *(const f32x2*)(ck + c0 + 2 * e), w1 = *(const f32x2*)(ck + D + c0 + 2 * e), w2 = *(const f32x2*)(ck + 2 * D + c0 + 2 * e);
;                 const float lo = bflo(bq[hf][e]) * (w0[0] * (bflo(cp[hf][e]) * bflo(vp[hf][e])) + w1[0] * (bflo(cq[hf][e]) * bflo(vq[hf][e])) + w2[0] * (bflo(cn[hf][e]) * bflo(vn[hf][e])));
;                 const float hi = bfhi(bq[hf][e]) * (w0[1] * (bfhi(cp[hf][e]) * bfhi(vp[hf][e])) + w1[1] * (bfhi(cq[hf][e]) * bfhi(vq[hf][e])) + w2[1] * (bfhi(cn[hf][e]) * bfhi(vn[hf][e])));
;                 ow[e] = cvt_pk_bf16(lo, hi);
;             }
;             *(u32x4*)(H + (size_t)row * D + c0) = ow;
.LBB0_893:
	s_andn2_b64 vcc, exec, s[4:5]
	s_cbranch_vccnz .LBB0_906
	s_cmp_ge_i32 s16, s65
	v_mov_b32_e32 v0, v196
	s_cbranch_scc1 .LBB0_906
	s_load_dwordx2 s[0:1], s[62:63], 0x50
	s_lshl_b64 s[4:5], s[72:73], 12
	v_lshlrev_b32_e32 v1, 6, v0
	v_and_b32_e32 v96, 0xfc0, v1
	v_and_b32_e32 v0, 63, v0
	s_waitcnt lgkmcnt(0)
	s_add_u32 s0, s0, s4
	s_addc_u32 s1, s1, s5
	s_add_u32 s4, s0, 0x2000
	s_addc_u32 s5, s1, 0
	v_lshl_add_u64 v[56:57], s[0:1], 0, v[96:97]
	s_add_u32 s0, s0, 0x1000
	s_addc_u32 s1, s1, 0
	v_lshl_add_u64 v[58:59], s[0:1], 0, v[96:97]
	s_waitcnt vmcnt(0)
	v_lshl_add_u64 v[60:61], s[4:5], 0, v[96:97]
	v_or_b32_e32 v96, 32, v96
	s_ashr_i32 s17, s16, 31
	v_lshl_add_u64 v[62:63], s[0:1], 0, v[96:97]
	s_lshl_b64 s[0:1], s[16:17], 11
	v_lshl_add_u64 v[64:65], s[4:5], 0, v[96:97]
	s_add_u32 s4, s54, s0
	s_addc_u32 s5, s55, s1
	s_mul_i32 s1, s16, 0x1800
	s_mul_hi_i32 s0, s16, 0x1800
	s_add_u32 s6, s54, s1
	v_lshlrev_b32_e32 v96, 5, v0
	s_addc_u32 s7, s55, s0
	s_mov_b32 s0, s16
	global_load_dwordx4 v[132:135], v[56:57], off
	global_load_dwordx4 v[136:139], v[56:57], off offset:16
	global_load_dwordx4 v[140:143], v[56:57], off offset:32
	global_load_dwordx4 v[144:147], v[56:57], off offset:48
	global_load_dwordx4 v[160:163], v[58:59], off
	global_load_dwordx4 v[164:167], v[58:59], off offset:16
	global_load_dwordx4 v[168:171], v[58:59], off offset:32
	global_load_dwordx4 v[172:175], v[58:59], off offset:48
	global_load_dwordx4 v[98:101], v[60:61], off
	global_load_dwordx4 v[102:105], v[60:61], off offset:16
	global_load_dwordx4 v[106:109], v[60:61], off offset:32
	global_load_dwordx4 v[110:113], v[60:61], off offset:48
	s_branch .LBB0_897
.LBB0_896:
	s_waitcnt vmcnt(0)
	v_mov_b64_e32 v[66:67], v[132:133]
	v_mov_b64_e32 v[68:69], v[160:161]
	v_mov_b64_e32 v[70:71], v[98:99]
	v_lshlrev_b32_e32 v73, 16, v44
	v_lshlrev_b32_e32 v72, 16, v52
	v_lshlrev_b32_e32 v75, 16, v40
	v_lshlrev_b32_e32 v74, 16, v48
	v_lshlrev_b32_e32 v77, 16, v28
	v_lshlrev_b32_e32 v78, 16, v36
	v_pk_mul_f32 v[72:73], v[74:75], v[72:73]
	v_lshlrev_b32_e32 v76, 16, v32
	v_and_b32_e32 v36, 0xffff0000, v36
	v_and_b32_e32 v28, 0xffff0000, v28
	v_mul_f32_e32 v28, v36, v28
	v_and_b32_e32 v32, 0xffff0000, v32
	v_lshlrev_b32_e32 v36, 16, v29
	v_and_b32_e32 v29, 0xffff0000, v29
	s_mov_b32 s1, 0x7000000
	s_add_i32 s0, s0, s26
	v_readlane_b32 s8, v254, 11
	v_readlane_b32 s9, v254, 12
	v_mov_b32_e32 v75, v66
	v_mul_f32_e32 v66, v78, v77
	v_mov_b32_e32 v74, v70
	v_pk_mul_f32 v[72:73], v[72:73], v[74:75]
	v_and_b32_e32 v75, 0xffff0000, v40
	v_fma_f32 v66, v66, v68, v73
	v_add_f32_e32 v66, v72, v66
	v_and_b32_e32 v73, 0xffff0000, v44
	v_and_b32_e32 v72, 0xffff0000, v52
	v_and_b32_e32 v74, 0xffff0000, v48
	v_mul_f32_e32 v68, v66, v76
	v_pk_mul_f32 v[72:73], v[74:75], v[72:73]
	v_mov_b32_e32 v66, v71
	v_pk_mul_f32 v[66:67], v[72:73], v[66:67]
	v_lshlrev_b32_e32 v73, 16, v45
	v_fma_f32 v28, v28, v69, v67
	v_add_f32_e32 v28, v66, v28
	v_mul_f32_e32 v28, v28, v32
	v_cvt_pk_bf16_f32 v28, v68, v28
	v_mov_b64_e32 v[66:67], v[134:135]
	v_mov_b64_e32 v[68:69], v[162:163]
	v_mov_b64_e32 v[70:71], v[100:101]
	v_lshlrev_b32_e32 v72, 16, v53
	v_lshlrev_b32_e32 v75, 16, v41
	v_lshlrev_b32_e32 v74, 16, v49
	v_lshlrev_b32_e32 v40, 16, v37
	v_pk_mul_f32 v[72:73], v[74:75], v[72:73]
	v_mul_f32_e32 v36, v40, v36
	v_lshlrev_b32_e32 v32, 16, v33
	v_and_b32_e32 v44, 0xffff0000, v33
	v_and_b32_e32 v48, 0xffff0000, v37
	v_and_b32_e32 v33, 0xffff0000, v45
	v_and_b32_e32 v37, 0xffff0000, v41
	v_mul_f32_e32 v29, v48, v29
	v_lshlrev_b32_e32 v45, 16, v46
	v_lshlrev_b32_e32 v48, 16, v50
	v_lshlrev_b32_e32 v52, 16, v34
	v_and_b32_e32 v34, 0xffff0000, v34
	v_mov_b32_e32 v75, v66
	v_mov_b32_e32 v74, v70
	v_pk_mul_f32 v[72:73], v[72:73], v[74:75]
	v_mov_b32_e32 v66, v71
	v_fma_f32 v36, v36, v68, v73
	v_add_f32_e32 v36, v72, v36
	v_mul_f32_e32 v40, v36, v32
	v_and_b32_e32 v32, 0xffff0000, v53
	v_and_b32_e32 v36, 0xffff0000, v49
	v_pk_mul_f32 v[32:33], v[36:37], v[32:33]
	v_lshlrev_b32_e32 v49, 16, v42
	v_pk_mul_f32 v[32:33], v[32:33], v[66:67]
	v_lshlrev_b32_e32 v53, 16, v30
	v_fma_f32 v29, v29, v69, v33
	v_add_f32_e32 v29, v32, v29
	v_mul_f32_e32 v29, v29, v44
	v_cvt_pk_bf16_f32 v29, v40, v29
	v_mov_b64_e32 v[32:33], v[136:137]
	v_mov_b64_e32 v[36:37], v[164:165]
	v_mov_b64_e32 v[40:41], v[102:103]
	v_lshlrev_b32_e32 v44, 16, v54
	v_lshlrev_b32_e32 v66, 16, v38
	v_pk_mul_f32 v[44:45], v[48:49], v[44:45]
	v_and_b32_e32 v38, 0xffff0000, v38
	v_and_b32_e32 v30, 0xffff0000, v30
	v_mul_f32_e32 v30, v38, v30
	v_lshlrev_b32_e32 v38, 16, v31
	v_and_b32_e32 v31, 0xffff0000, v31
	v_mov_b32_e32 v49, v32
	v_mul_f32_e32 v32, v66, v53
	v_mov_b32_e32 v48, v40
	v_pk_mul_f32 v[44:45], v[44:45], v[48:49]
	v_and_b32_e32 v49, 0xffff0000, v42
	v_fma_f32 v32, v32, v36, v45
	v_add_f32_e32 v32, v44, v32
	v_and_b32_e32 v45, 0xffff0000, v46
	v_and_b32_e32 v44, 0xffff0000, v54
	v_and_b32_e32 v48, 0xffff0000, v50
	v_mul_f32_e32 v36, v32, v52
	v_pk_mul_f32 v[44:45], v[48:49], v[44:45]
	v_mov_b32_e32 v32, v41
	v_pk_mul_f32 v[32:33], v[44:45], v[32:33]
	v_lshlrev_b32_e32 v45, 16, v47
	v_fma_f32 v30, v30, v37, v33
	v_add_f32_e32 v30, v32, v30
	v_mul_f32_e32 v30, v30, v34
	v_cvt_pk_bf16_f32 v30, v36, v30
	v_mov_b64_e32 v[32:33], v[138:139]
	v_mov_b64_e32 v[36:37], v[166:167]
	v_mov_b64_e32 v[40:41], v[104:105]
	v_lshlrev_b32_e32 v44, 16, v55
	v_lshlrev_b32_e32 v49, 16, v43
	v_lshlrev_b32_e32 v48, 16, v51
	v_lshlrev_b32_e32 v42, 16, v39
; __device__ __forceinline__ unsigned cvt_pk_bf16(float lo, float hi) { unsigned r; asm volatile("v_cvt_pk_bf16_f32 %0, %1, %2" : "=v"(r) : "v"(lo), "v"(hi)); return r; }
; __device__ __forceinline__ float bflo(unsigned w) { return __uint_as_float(w << 16); }
; __device__ __forceinline__ float bfhi(unsigned w) { return __uint_as_float(w & 0xffff0000u); }
; __device__ __forceinline__ void convgate_phase(const bf16_t* U, bf16_t* H, int rows, const float* ck, int gw, int NGW, int lane) {
;     ...
; #pragma unroll
;         for (int hf = 0; hf < 2; ++hf) {
;             const int c0 = lane * 16 + hf * 8;
;             u32x4 ow;
; #pragma unroll
;             for (int e = 0; e < 4; ++e) {
;                 const f32x2 w0 = *(const f32x2*)(ck + c0 + 2 * e), w1 = *(const f32x2*)(ck + D + c0 + 2 * e), w2 = *(const f32x2*)(ck + 2 * D + c0 + 2 * e);
;                 const float lo = bflo(bq[hf][e]) * (w0[0] * (bflo(cp[hf][e]) * bflo(vp[hf][e])) + w1[0] * (bflo(cq[hf][e]) * bflo(vq[hf][e])) + w2[0] * (bflo(cn[hf][e]) * bflo(vn[hf][e])));
;                 const float hi = bfhi(bq[hf][e]) * (w0[1] * (bfhi(cp[hf][e]) * bfhi(vp[hf][e])) + w1[1] * (bfhi(cq[hf][e]) * bfhi(vq[hf][e])) + w2[1] * (bfhi(cn[hf][e]) * bfhi(vn[hf][e])));
;                 ow[e] = cvt_pk_bf16(lo, hi);
;             }
;             *(u32x4*)(H + (size_t)row * D + c0) = ow;
;         }
	v_pk_mul_f32 v[44:45], v[48:49], v[44:45]
	v_lshlrev_b32_e32 v34, 16, v35
	v_mov_b32_e32 v49, v32
	v_mul_f32_e32 v32, v42, v38
	v_mov_b32_e32 v48, v40
	v_pk_mul_f32 v[44:45], v[44:45], v[48:49]
	v_and_b32_e32 v40, 0xffff0000, v35
	v_fma_f32 v32, v32, v36, v45
	v_add_f32_e32 v32, v44, v32
	v_mul_f32_e32 v36, v32, v34
	v_and_b32_e32 v42, 0xffff0000, v39
	v_and_b32_e32 v35, 0xffff0000, v47
	v_and_b32_e32 v34, 0xffff0000, v55
	v_and_b32_e32 v39, 0xffff0000, v43
	v_and_b32_e32 v38, 0xffff0000, v51
	v_pk_mul_f32 v[34:35], v[38:39], v[34:35]
	v_mov_b32_e32 v32, v41
	v_pk_mul_f32 v[32:33], v[34:35], v[32:33]
	v_mul_f32_e32 v31, v42, v31
	v_fma_f32 v31, v31, v37, v33
	v_add_f32_e32 v31, v32, v31
	v_lshl_add_u64 v[32:33], s[4:5], 0, v[96:97]
	v_add_co_u32_e32 v32, vcc, s1, v32
	v_mul_f32_e32 v31, v31, v40
	s_nop 0
	v_addc_co_u32_e32 v33, vcc, 0, v33, vcc
	v_cvt_pk_bf16_f32 v31, v36, v31
	global_store_dwordx4 v[32:33], v[28:31], off
	s_nop 1
	v_mov_b64_e32 v[28:29], v[140:141]
	s_nop 0
	v_mov_b64_e32 v[30:31], v[168:169]
	v_mov_b64_e32 v[34:35], v[106:107]
	v_lshlrev_b32_e32 v37, 16, v16
	v_lshlrev_b32_e32 v36, 16, v24
	v_lshlrev_b32_e32 v39, 16, v0
	v_lshlrev_b32_e32 v38, 16, v20
	v_lshlrev_b32_e32 v41, 16, v4
	v_lshlrev_b32_e32 v42, 16, v12
	v_pk_mul_f32 v[36:37], v[38:39], v[36:37]
	v_lshlrev_b32_e32 v40, 16, v8
	v_and_b32_e32 v12, 0xffff0000, v12
	v_and_b32_e32 v4, 0xffff0000, v4
	v_and_b32_e32 v8, 0xffff0000, v8
	s_add_u32 s4, s4, s8
	s_addc_u32 s5, s5, s9
	s_mul_i32 s1, s18, 0xc000
	s_add_u32 s6, s6, s1
	s_mul_hi_i32 s1, s26, 0x1800
	s_addc_u32 s7, s7, s1
	s_cmp_ge_i32 s0, s65
	v_mov_b32_e32 v39, v28
	v_mul_f32_e32 v28, v42, v41
	v_mov_b32_e32 v38, v34
	v_pk_mul_f32 v[36:37], v[36:37], v[38:39]
	v_and_b32_e32 v39, 0xffff0000, v0
	v_fma_f32 v28, v28, v30, v37
	v_add_f32_e32 v28, v36, v28
	v_and_b32_e32 v37, 0xffff0000, v16
	v_and_b32_e32 v36, 0xffff0000, v24
	v_and_b32_e32 v38, 0xffff0000, v20
	v_mul_f32_e32 v30, v28, v40
	v_pk_mul_f32 v[36:37], v[38:39], v[36:37]
	v_mov_b32_e32 v28, v35
	v_pk_mul_f32 v[28:29], v[36:37], v[28:29]
	v_mul_f32_e32 v0, v12, v4
	v_fma_f32 v0, v0, v31, v29
	v_add_f32_e32 v0, v28, v0
	v_mul_f32_e32 v0, v0, v8
	v_cvt_pk_bf16_f32 v0, v30, v0
	v_mov_b64_e32 v[28:29], v[142:143]
	v_mov_b64_e32 v[30:31], v[170:171]
	v_mov_b64_e32 v[34:35], v[108:109]
	v_lshlrev_b32_e32 v37, 16, v17
	v_lshlrev_b32_e32 v36, 16, v25
	v_lshlrev_b32_e32 v39, 16, v1
	v_lshlrev_b32_e32 v38, 16, v21
	v_lshlrev_b32_e32 v8, 16, v5
	v_lshlrev_b32_e32 v12, 16, v13
	v_pk_mul_f32 v[36:37], v[38:39], v[36:37]
	v_mul_f32_e32 v8, v12, v8
	v_lshlrev_b32_e32 v4, 16, v9
	v_and_b32_e32 v16, 0xffff0000, v9
	v_and_b32_e32 v20, 0xffff0000, v5
	v_and_b32_e32 v5, 0xffff0000, v17
	v_and_b32_e32 v9, 0xffff0000, v1
	v_and_b32_e32 v13, 0xffff0000, v13
	v_mul_f32_e32 v1, v13, v20
	v_lshlrev_b32_e32 v17, 16, v18
	v_lshlrev_b32_e32 v20, 16, v22
	v_lshlrev_b32_e32 v24, 16, v10
	v_and_b32_e32 v10, 0xffff0000, v10
	v_mov_b32_e32 v39, v28
	v_mov_b32_e32 v38, v34
	v_pk_mul_f32 v[36:37], v[36:37], v[38:39]
	v_mov_b32_e32 v28, v35
	v_fma_f32 v8, v8, v30, v37
	v_add_f32_e32 v8, v36, v8
	v_mul_f32_e32 v12, v8, v4
	v_and_b32_e32 v4, 0xffff0000, v25
	v_and_b32_e32 v8, 0xffff0000, v21
	v_pk_mul_f32 v[4:5], v[8:9], v[4:5]
	v_lshlrev_b32_e32 v21, 16, v2
	v_pk_mul_f32 v[4:5], v[4:5], v[28:29]
	v_lshlrev_b32_e32 v25, 16, v6
	v_fma_f32 v1, v1, v31, v5
	v_add_f32_e32 v1, v4, v1
	v_mul_f32_e32 v1, v1, v16
	v_cvt_pk_bf16_f32 v1, v12, v1
	v_mov_b64_e32 v[4:5], v[144:145]
	v_mov_b64_e32 v[8:9], v[172:173]
	v_mov_b64_e32 v[12:13], v[110:111]
	v_lshlrev_b32_e32 v16, 16, v26
	v_lshlrev_b32_e32 v28, 16, v14
	v_pk_mul_f32 v[16:17], v[20:21], v[16:17]
	v_and_b32_e32 v6, 0xffff0000, v6
	v_mov_b32_e32 v21, v4
	v_mul_f32_e32 v4, v28, v25
	v_mov_b32_e32 v20, v12
	v_pk_mul_f32 v[16:17], v[16:17], v[20:21]
	v_and_b32_e32 v21, 0xffff0000, v2
	v_fma_f32 v4, v4, v8, v17
	v_add_f32_e32 v4, v16, v4
	v_and_b32_e32 v17, 0xffff0000, v18
	v_and_b32_e32 v16, 0xffff0000, v26
	v_and_b32_e32 v20, 0xffff0000, v22
	v_mul_f32_e32 v8, v4, v24
	v_and_b32_e32 v12, 0xffff0000, v14
	v_pk_mul_f32 v[16:17], v[20:21], v[16:17]
	v_mov_b32_e32 v4, v13
	v_pk_mul_f32 v[4:5], v[16:17], v[4:5]
	v_mul_f32_e32 v2, v12, v6
	v_fma_f32 v2, v2, v9, v5
	v_add_f32_e32 v2, v4, v2
	v_mul_f32_e32 v2, v2, v10
	v_cvt_pk_bf16_f32 v2, v8, v2
	v_mov_b64_e32 v[4:5], v[146:147]
	v_mov_b64_e32 v[8:9], v[174:175]
	v_mov_b64_e32 v[12:13], v[112:113]
	v_lshlrev_b32_e32 v17, 16, v19
	v_lshlrev_b32_e32 v16, 16, v27
	v_lshlrev_b32_e32 v21, 16, v3
	v_lshlrev_b32_e32 v20, 16, v23
	v_lshlrev_b32_e32 v10, 16, v7
	v_lshlrev_b32_e32 v14, 16, v15
	v_pk_mul_f32 v[16:17], v[20:21], v[16:17]
	v_lshlrev_b32_e32 v6, 16, v11
	v_mov_b32_e32 v21, v4
	v_mul_f32_e32 v4, v14, v10
	v_mov_b32_e32 v20, v12
	v_pk_mul_f32 v[16:17], v[16:17], v[20:21]
	v_and_b32_e32 v12, 0xffff0000, v11
	v_fma_f32 v4, v4, v8, v17
	v_add_f32_e32 v4, v16, v4
	v_mul_f32_e32 v8, v4, v6
	v_and_b32_e32 v14, 0xffff0000, v15
	v_and_b32_e32 v15, 0xffff0000, v7
	v_and_b32_e32 v7, 0xffff0000, v19
	v_and_b32_e32 v6, 0xffff0000, v27
	v_and_b32_e32 v11, 0xffff0000, v3
	v_and_b32_e32 v10, 0xffff0000, v23
	v_pk_mul_f32 v[6:7], v[10:11], v[6:7]
	v_mov_b32_e32 v4, v13
	v_pk_mul_f32 v[4:5], v[6:7], v[4:5]
	v_mul_f32_e32 v3, v14, v15
	v_fma_f32 v3, v3, v9, v5
	v_add_f32_e32 v3, v4, v3
	v_mul_f32_e32 v3, v3, v12
	v_cvt_pk_bf16_f32 v3, v8, v3
	global_store_dwordx4 v[32:33], v[0:3], off offset:16
	s_cbranch_scc1 .LBB0_906
